# SWIGLU GEMM K-loop rotated: next K-step LDS-DMA issued between second-half MFMAs, SGPR-base DMA addressing
# speedup vs baseline: 1.1859x; 1.0060x over previous
;     ...
;     } else {
;       const bf16_t* ap = A + (size_t)(m0 + lrow) * lda + lsw;
;       const bf16_t* bp = Wt + (size_t)(n0 + lrow) * K + lsw;
;       const size_t a32 = (size_t)32 * lda, b32 = (size_t)32 * K;
;       typedef __attribute__((address_space(3))) unsigned lds_u32;
;       lds_u32* sbase = (lds_u32*)(smem) + wave * 256;
;       for (int kt = 0; kt < KT; kt++) {
;         {
;           const bf16_t* apx = ap;
;           int kc = kt * 64;
;           if (SHIFT && kc >= 1024) { apx = ap - lda; kc -= 1024; }
; #pragma unroll
;           for (int i = 0; i < 8; i++)
;             __builtin_amdgcn_global_load_lds((const unsigned*)(apx + i * a32 + kc), sbase + i * 1024, 16, 0, 0);
; #pragma unroll
;           for (int i = 0; i < 4; i++)
;             __builtin_amdgcn_global_load_lds((const unsigned*)(bp + i * b32 + kt * 64), sbase + 8192 + i * 1024, 16, 0, 0);
;         }
.LBB0_2625:
	s_lshl_b32 s7, s9, 8
	v_add_u32_e32 v10, s7, v146
	v_ashrrev_i32_e32 v11, 31, v10
	s_lshl_b32 s8, s8, 7
	v_lshlrev_b64 v[10:11], 11, v[10:11]
	v_lshl_add_u64 v[142:143], v[138:139], 0, v[10:11]
	v_add_u32_e32 v10, s8, v146
	v_ashrrev_i32_e32 v11, 31, v10
	v_lshlrev_b64 v[10:11], 11, v[10:11]
	v_lshl_add_u64 v[144:145], v[140:141], 0, v[10:11]
	v_mov_b32_e32 v10, 0
	s_mov_b64 s[4:5], 0
	v_mov_b32_e32 v11, v10
	v_mov_b32_e32 v12, v10
	v_mov_b32_e32 v13, v10
	v_mov_b32_e32 v14, v10
	v_mov_b32_e32 v15, v10
	v_mov_b32_e32 v16, v10
	v_mov_b32_e32 v17, v10
	v_mov_b32_e32 v18, v10
	v_mov_b32_e32 v19, v10
	v_mov_b32_e32 v20, v10
	v_mov_b32_e32 v21, v10
	v_mov_b32_e32 v22, v10
	v_mov_b32_e32 v23, v10
	v_mov_b32_e32 v24, v10
	v_mov_b32_e32 v25, v10
	v_mov_b32_e32 v26, v10
	v_mov_b32_e32 v27, v10
	v_mov_b32_e32 v28, v10
	v_mov_b32_e32 v29, v10
	v_mov_b32_e32 v30, v10
	v_mov_b32_e32 v31, v10
	v_mov_b32_e32 v32, v10
	v_mov_b32_e32 v33, v10
	v_mov_b32_e32 v34, v10
	v_mov_b32_e32 v35, v10
	v_mov_b32_e32 v36, v10
	v_mov_b32_e32 v37, v10
	v_mov_b32_e32 v38, v10
	v_mov_b32_e32 v39, v10
	v_mov_b32_e32 v40, v10
	v_mov_b32_e32 v41, v10
	v_mov_b32_e32 v42, v10
	v_mov_b32_e32 v43, v10
	v_mov_b32_e32 v44, v10
	v_mov_b32_e32 v45, v10
	v_mov_b32_e32 v46, v10
	v_mov_b32_e32 v47, v10
	v_mov_b32_e32 v48, v10
	v_mov_b32_e32 v49, v10
	v_mov_b32_e32 v50, v10
	v_mov_b32_e32 v51, v10
	v_mov_b32_e32 v52, v10
	v_mov_b32_e32 v53, v10
	v_mov_b32_e32 v54, v10
	v_mov_b32_e32 v55, v10
	v_mov_b32_e32 v56, v10
	v_mov_b32_e32 v57, v10
	v_mov_b32_e32 v58, v10
	v_mov_b32_e32 v59, v10
	v_mov_b32_e32 v60, v10
	v_mov_b32_e32 v61, v10
	v_mov_b32_e32 v62, v10
	v_mov_b32_e32 v63, v10
	v_mov_b32_e32 v64, v10
	v_mov_b32_e32 v65, v10
	v_mov_b32_e32 v66, v10
	v_mov_b32_e32 v67, v10
	v_mov_b32_e32 v68, v10
	v_mov_b32_e32 v69, v10
	v_mov_b32_e32 v70, v10
	v_mov_b32_e32 v71, v10
	v_mov_b32_e32 v72, v10
	v_mov_b32_e32 v73, v10
	v_mov_b32_e32 v74, v10
	v_mov_b32_e32 v75, v10
	v_mov_b32_e32 v76, v10
	v_mov_b32_e32 v77, v10
	v_mov_b32_e32 v78, v10
	v_mov_b32_e32 v79, v10
	v_mov_b32_e32 v80, v10
	v_mov_b32_e32 v81, v10
	v_mov_b32_e32 v82, v10
	v_mov_b32_e32 v83, v10
	v_mov_b32_e32 v84, v10
	v_mov_b32_e32 v85, v10
	v_mov_b32_e32 v86, v10
	v_mov_b32_e32 v87, v10
	v_mov_b32_e32 v88, v10
	v_mov_b32_e32 v89, v10
	v_mov_b32_e32 v90, v10
	v_mov_b32_e32 v91, v10
	v_mov_b32_e32 v92, v10
	v_mov_b32_e32 v93, v10
	v_mov_b32_e32 v94, v10
	v_mov_b32_e32 v95, v10
	v_mov_b32_e32 v96, v10
	v_mov_b32_e32 v97, v10
	v_mov_b32_e32 v98, v10
	v_mov_b32_e32 v99, v10
	v_mov_b32_e32 v100, v10
	v_mov_b32_e32 v101, v10
	v_mov_b32_e32 v102, v10
	v_mov_b32_e32 v103, v10
	v_mov_b32_e32 v104, v10
	v_mov_b32_e32 v105, v10
	v_mov_b32_e32 v106, v10
	v_mov_b32_e32 v107, v10
	v_mov_b32_e32 v108, v10
	v_mov_b32_e32 v109, v10
	v_mov_b32_e32 v110, v10
	v_mov_b32_e32 v111, v10
	v_mov_b32_e32 v112, v10
	v_mov_b32_e32 v113, v10
	v_mov_b32_e32 v114, v10
	v_mov_b32_e32 v115, v10
	v_mov_b32_e32 v116, v10
	v_mov_b32_e32 v117, v10
	v_mov_b32_e32 v118, v10
	v_mov_b32_e32 v119, v10
	v_mov_b32_e32 v120, v10
	v_mov_b32_e32 v121, v10
	v_mov_b32_e32 v122, v10
	v_mov_b32_e32 v123, v10
	v_mov_b32_e32 v124, v10
	v_mov_b32_e32 v125, v10
	v_mov_b32_e32 v126, v10
	v_mov_b32_e32 v127, v10
	v_mov_b32_e32 v128, v10
	v_mov_b32_e32 v129, v10
	v_mov_b32_e32 v130, v10
	v_mov_b32_e32 v131, v10
	v_mov_b32_e32 v132, v10
	v_mov_b32_e32 v133, v10
	v_mov_b32_e32 v134, v10
	v_mov_b32_e32 v135, v10
	v_mov_b32_e32 v136, v10
	v_mov_b32_e32 v137, v10
	v_lshrrev_b32_e32 v239, 3, v2
	v_and_b32_e32 v239, 7, v239
	v_lshrrev_b32_e32 v240, 4, v2
	v_xor_b32_e32 v240, v240, v2
	v_and_b32_e32 v240, 7, v240
	v_lshlrev_b32_e32 v240, 4, v240
	v_mov_b32_e32 v241, 0x800
	v_mad_u32_u24 v238, v239, v241, v240
	v_sub_co_u32_e32 v240, vcc, v142, v238
	s_nop 1
	v_subbrev_co_u32_e32 v241, vcc, 0, v143, vcc
	v_readfirstlane_b32 s9, v147
	v_readfirstlane_b32 s10, v240
	v_readfirstlane_b32 s11, v241
	s_add_u32 s12, s10, 0x800
	s_addc_u32 s13, s11, 0
	s_add_u32 s14, s10, 0x10800
	s_addc_u32 s15, s11, 0
	s_add_u32 s16, s10, 0x20800
	s_addc_u32 s17, s11, 0
	s_add_u32 s18, s10, 0x30800
	s_addc_u32 s19, s11, 0
	s_add_u32 s20, s10, 0x40800
	s_addc_u32 s21, s11, 0
	s_add_u32 s22, s10, 0x50800
	s_addc_u32 s23, s11, 0
	s_add_u32 s24, s10, 0x60800
	s_addc_u32 s25, s11, 0
	s_add_u32 s26, s10, 0x70800
	s_addc_u32 s27, s11, 0
	v_mov_b32_e32 v230, v144
	v_mov_b32_e32 v231, v145
	s_mov_b64 s[10:11], 0x10000
	v_lshl_add_u64 v[232:233], v[144:145], 0, s[10:11]
	s_mov_b64 s[10:11], 0x20000
	v_lshl_add_u64 v[234:235], v[144:145], 0, s[10:11]
	s_mov_b64 s[10:11], 0x30000
	v_lshl_add_u64 v[236:237], v[144:145], 0, s[10:11]
	s_mov_b64 s[10:11], 0x80
	s_mov_b32 m0, s9
	s_nop 0
	global_load_lds_dwordx4 v238, s[12:13]
	s_add_u32 m0, s9, 0x1000
	s_nop 0
	global_load_lds_dwordx4 v238, s[14:15]
	s_add_u32 m0, s9, 0x2000
	s_nop 0
	global_load_lds_dwordx4 v238, s[16:17]
	s_add_u32 m0, s9, 0x3000
	s_nop 0
	global_load_lds_dwordx4 v238, s[18:19]
	s_add_u32 m0, s9, 0x4000
	s_nop 0
	global_load_lds_dwordx4 v238, s[20:21]
	s_add_u32 m0, s9, 0x5000
	s_nop 0
	global_load_lds_dwordx4 v238, s[22:23]
	s_add_u32 m0, s9, 0x6000
	s_nop 0
	global_load_lds_dwordx4 v238, s[24:25]
	s_add_u32 m0, s9, 0x7000
	s_nop 0
	global_load_lds_dwordx4 v238, s[26:27]
	s_add_u32 m0, s9, 0x8000
	s_nop 0
	global_load_lds_dwordx4 v[230:231], off
	s_add_u32 m0, s9, 0x9000
	s_nop 0
	global_load_lds_dwordx4 v[232:233], off
	s_add_u32 m0, s9, 0xa000
	s_nop 0
	global_load_lds_dwordx4 v[234:235], off
	s_add_u32 m0, s9, 0xb000
	s_nop 0
	global_load_lds_dwordx4 v[236:237], off
;     ...
;       for (int kt = 0; kt < KT; kt++) {
;         {
;           const bf16_t* apx = ap;
;           int kc = kt * 64;
;           if (SHIFT && kc >= 1024) { apx = ap - lda; kc -= 1024; }
; #pragma unroll
;           for (int i = 0; i < 8; i++)
;             __builtin_amdgcn_global_load_lds((const unsigned*)(apx + i * a32 + kc), sbase + i * 1024, 16, 0, 0);
; #pragma unroll
;           for (int i = 0; i < 4; i++)
;             __builtin_amdgcn_global_load_lds((const unsigned*)(bp + i * b32 + kt * 64), sbase + 8192 + i * 1024, 16, 0, 0);
;         }
;         asm volatile("s_waitcnt vmcnt(0)" ::: "memory");
;         __syncthreads();
; #pragma unroll
;         for (int kk = 0; kk < 2; kk++) {
;           bf16x8 af[MI], bfr[4];
;           const int csw = (((kk * 4 + fq) ^ fsw) << 3);
; #pragma unroll
;           for (int mi = 0; mi < MI; mi++) af[mi] = *(const bf16x8*)(smem + (wm * 128 + mi * 16 + fr) * 64 + csw);
; #pragma unroll
;           for (int ni = 0; ni < 4; ni++) bfr[ni] = *(const bf16x8*)(smem + 16384 + (wn * 64 + ni * 16 + fr) * 64 + csw);
; #pragma unroll
;           for (int mi = 0; mi < MI; mi++)
; #pragma unroll
;             for (int ni = 0; ni < 4; ni++)
;               acc[mi][ni] = __builtin_amdgcn_mfma_f32_16x16x32_bf16(bfr[ni], af[mi], acc[mi][ni], 0, 0, 0);
;         }
;         __syncthreads();
;       }
.Lsw_loop:
	s_waitcnt vmcnt(0)
	s_barrier
	v_add_u32_e32 v8, v151, v152
	ds_read_b128 v[156:159], v8
	ds_read_b128 v[166:169], v8 offset:2048
	ds_read_b128 v[170:173], v8 offset:4096
	ds_read_b128 v[174:177], v8 offset:6144
	ds_read_b128 v[178:181], v8 offset:8192
	ds_read_b128 v[182:185], v8 offset:10240
	ds_read_b128 v[186:189], v8 offset:12288
	ds_read_b128 v[190:193], v8 offset:14336
	ds_read_b128 v[194:197], v154 offset:32768
	ds_read_b128 v[198:201], v154 offset:34816
	ds_read_b128 v[202:205], v154 offset:36864
	ds_read_b128 v[226:229], v154 offset:38912
	v_add_u32_e32 v8, v153, v152
	s_waitcnt lgkmcnt(3)
	v_mfma_f32_16x16x32_bf16 v[134:137], v[194:197], v[156:159], v[134:137]
	s_add_u32 s4, s4, 0x80
	s_addc_u32 s5, s5, 0
	s_cmpk_eq_i32 s4, 0x800
	s_waitcnt lgkmcnt(2)
	v_mfma_f32_16x16x32_bf16 v[130:133], v[198:201], v[156:159], v[130:133]
	s_waitcnt lgkmcnt(1)
	v_mfma_f32_16x16x32_bf16 v[126:129], v[202:205], v[156:159], v[126:129]
	s_waitcnt lgkmcnt(0)
	v_mfma_f32_16x16x32_bf16 v[122:125], v[226:229], v[156:159], v[122:125]
	v_mfma_f32_16x16x32_bf16 v[118:121], v[194:197], v[166:169], v[118:121]
	v_mfma_f32_16x16x32_bf16 v[114:117], v[198:201], v[166:169], v[114:117]
	v_mfma_f32_16x16x32_bf16 v[110:113], v[202:205], v[166:169], v[110:113]
	v_mfma_f32_16x16x32_bf16 v[106:109], v[226:229], v[166:169], v[106:109]
	v_mfma_f32_16x16x32_bf16 v[102:105], v[194:197], v[170:173], v[102:105]
	v_mfma_f32_16x16x32_bf16 v[98:101], v[198:201], v[170:173], v[98:101]
	v_mfma_f32_16x16x32_bf16 v[94:97], v[202:205], v[170:173], v[94:97]
	v_mfma_f32_16x16x32_bf16 v[90:93], v[226:229], v[170:173], v[90:93]
	v_mfma_f32_16x16x32_bf16 v[86:89], v[194:197], v[174:177], v[86:89]
	v_mfma_f32_16x16x32_bf16 v[82:85], v[198:201], v[174:177], v[82:85]
	v_mfma_f32_16x16x32_bf16 v[78:81], v[202:205], v[174:177], v[78:81]
	v_mfma_f32_16x16x32_bf16 v[74:77], v[226:229], v[174:177], v[74:77]
	v_mfma_f32_16x16x32_bf16 v[70:73], v[194:197], v[178:181], v[70:73]
	v_mfma_f32_16x16x32_bf16 v[66:69], v[198:201], v[178:181], v[66:69]
	v_mfma_f32_16x16x32_bf16 v[62:65], v[202:205], v[178:181], v[62:65]
	v_mfma_f32_16x16x32_bf16 v[58:61], v[226:229], v[178:181], v[58:61]
	v_mfma_f32_16x16x32_bf16 v[54:57], v[194:197], v[182:185], v[54:57]
	v_mfma_f32_16x16x32_bf16 v[50:53], v[198:201], v[182:185], v[50:53]
	v_mfma_f32_16x16x32_bf16 v[46:49], v[202:205], v[182:185], v[46:49]
	v_mfma_f32_16x16x32_bf16 v[42:45], v[226:229], v[182:185], v[42:45]
	v_mfma_f32_16x16x32_bf16 v[38:41], v[194:197], v[186:189], v[38:41]
	v_mfma_f32_16x16x32_bf16 v[34:37], v[198:201], v[186:189], v[34:37]
	v_mfma_f32_16x16x32_bf16 v[30:33], v[202:205], v[186:189], v[30:33]
	v_mfma_f32_16x16x32_bf16 v[26:29], v[226:229], v[186:189], v[26:29]
	v_mfma_f32_16x16x32_bf16 v[22:25], v[194:197], v[190:193], v[22:25]
	v_mfma_f32_16x16x32_bf16 v[18:21], v[198:201], v[190:193], v[18:21]
	v_mfma_f32_16x16x32_bf16 v[14:17], v[202:205], v[190:193], v[14:17]
	v_mfma_f32_16x16x32_bf16 v[10:13], v[226:229], v[190:193], v[10:13]
	ds_read_b128 v[156:159], v8
	ds_read_b128 v[166:169], v8 offset:2048
	ds_read_b128 v[170:173], v8 offset:4096
	ds_read_b128 v[174:177], v8 offset:6144
	ds_read_b128 v[178:181], v8 offset:8192
	ds_read_b128 v[182:185], v8 offset:10240
	ds_read_b128 v[186:189], v8 offset:12288
	ds_read_b128 v[190:193], v8 offset:14336
	ds_read_b128 v[194:197], v155 offset:32768
	ds_read_b128 v[198:201], v155 offset:34816
	ds_read_b128 v[202:205], v155 offset:36864
	ds_read_b128 v[226:229], v155 offset:38912
	s_waitcnt lgkmcnt(0)
	s_barrier
	s_cmpk_eq_i32 s4, 0x800
	s_cbranch_scc1 .Lsw_last
	v_add_u32_e32 v238, 0x80, v238
	v_lshl_add_u64 v[230:231], v[230:231], 0, s[10:11]
	v_lshl_add_u64 v[232:233], v[232:233], 0, s[10:11]
	v_lshl_add_u64 v[234:235], v[234:235], 0, s[10:11]
	v_lshl_add_u64 v[236:237], v[236:237], 0, s[10:11]
	v_mfma_f32_16x16x32_bf16 v[134:137], v[194:197], v[156:159], v[134:137]
	v_mfma_f32_16x16x32_bf16 v[130:133], v[198:201], v[156:159], v[130:133]
	v_mfma_f32_16x16x32_bf16 v[126:129], v[202:205], v[156:159], v[126:129]
	v_mfma_f32_16x16x32_bf16 v[122:125], v[226:229], v[156:159], v[122:125]
	v_mfma_f32_16x16x32_bf16 v[118:121], v[194:197], v[166:169], v[118:121]
	v_mfma_f32_16x16x32_bf16 v[114:117], v[198:201], v[166:169], v[114:117]
	s_mov_b32 m0, s9
	v_mfma_f32_16x16x32_bf16 v[110:113], v[202:205], v[166:169], v[110:113]
	global_load_lds_dwordx4 v238, s[12:13]
	v_mfma_f32_16x16x32_bf16 v[106:109], v[226:229], v[166:169], v[106:109]
	s_add_u32 m0, s9, 0x1000
	v_mfma_f32_16x16x32_bf16 v[102:105], v[194:197], v[170:173], v[102:105]
	global_load_lds_dwordx4 v238, s[14:15]
	v_mfma_f32_16x16x32_bf16 v[98:101], v[198:201], v[170:173], v[98:101]
	s_add_u32 m0, s9, 0x2000
	v_mfma_f32_16x16x32_bf16 v[94:97], v[202:205], v[170:173], v[94:97]
	global_load_lds_dwordx4 v238, s[16:17]
	v_mfma_f32_16x16x32_bf16 v[90:93], v[226:229], v[170:173], v[90:93]
	s_add_u32 m0, s9, 0x3000
	v_mfma_f32_16x16x32_bf16 v[86:89], v[194:197], v[174:177], v[86:89]
	global_load_lds_dwordx4 v238, s[18:19]
	v_mfma_f32_16x16x32_bf16 v[82:85], v[198:201], v[174:177], v[82:85]
	s_add_u32 m0, s9, 0x4000
	v_mfma_f32_16x16x32_bf16 v[78:81], v[202:205], v[174:177], v[78:81]
	global_load_lds_dwordx4 v238, s[20:21]
	v_mfma_f32_16x16x32_bf16 v[74:77], v[226:229], v[174:177], v[74:77]
	s_add_u32 m0, s9, 0x5000
	v_mfma_f32_16x16x32_bf16 v[70:73], v[194:197], v[178:181], v[70:73]
	global_load_lds_dwordx4 v238, s[22:23]
	v_mfma_f32_16x16x32_bf16 v[66:69], v[198:201], v[178:181], v[66:69]
	s_add_u32 m0, s9, 0x6000
	v_mfma_f32_16x16x32_bf16 v[62:65], v[202:205], v[178:181], v[62:65]
	global_load_lds_dwordx4 v238, s[24:25]
	v_mfma_f32_16x16x32_bf16 v[58:61], v[226:229], v[178:181], v[58:61]
	s_add_u32 m0, s9, 0x7000
	v_mfma_f32_16x16x32_bf16 v[54:57], v[194:197], v[182:185], v[54:57]
	global_load_lds_dwordx4 v238, s[26:27]
	v_mfma_f32_16x16x32_bf16 v[50:53], v[198:201], v[182:185], v[50:53]
	s_add_u32 m0, s9, 0x8000
	v_mfma_f32_16x16x32_bf16 v[46:49], v[202:205], v[182:185], v[46:49]
	global_load_lds_dwordx4 v[230:231], off
	v_mfma_f32_16x16x32_bf16 v[42:45], v[226:229], v[182:185], v[42:45]
	s_add_u32 m0, s9, 0x9000
	v_mfma_f32_16x16x32_bf16 v[38:41], v[194:197], v[186:189], v[38:41]
	global_load_lds_dwordx4 v[232:233], off
	v_mfma_f32_16x16x32_bf16 v[34:37], v[198:201], v[186:189], v[34:37]
	s_add_u32 m0, s9, 0xa000
	v_mfma_f32_16x16x32_bf16 v[30:33], v[202:205], v[186:189], v[30:33]
	global_load_lds_dwordx4 v[234:235], off
	v_mfma_f32_16x16x32_bf16 v[26:29], v[226:229], v[186:189], v[26:29]
	s_add_u32 m0, s9, 0xb000
	v_mfma_f32_16x16x32_bf16 v[22:25], v[194:197], v[190:193], v[22:25]
	global_load_lds_dwordx4 v[236:237], off
	v_mfma_f32_16x16x32_bf16 v[18:21], v[198:201], v[190:193], v[18:21]
	v_mfma_f32_16x16x32_bf16 v[14:17], v[202:205], v[190:193], v[14:17]
	v_mfma_f32_16x16x32_bf16 v[10:13], v[226:229], v[190:193], v[10:13]
	s_branch .Lsw_loop
; __device__ __forceinline__ float siluf_(float x) { return x * __builtin_amdgcn_rcpf(1.f + __expf(-x)); }
;     ...
; #pragma unroll
;             for (int ni = 0; ni < 4; ni++)
;               acc[mi][ni] = __builtin_amdgcn_mfma_f32_16x16x32_bf16(bfr[ni], af[mi], acc[mi][ni], 0, 0, 0);
;     ...
;         } else if constexpr (EPI == EPI_SWIGLU) {
; #pragma unroll
;           for (int np = 0; np < 2; np++) {
;             const unsigned hc = ((unsigned)(n0 + wn * 64) >> 1) + np * 16 + fq * 4;
;             const f32x4 g = acc[mi][2 * np], u = acc[mi][2 * np + 1];
;             uint2 o;
;             o.x = pack2(siluf_(g[0]) * u[0], siluf_(g[1]) * u[1]);
;             o.y = pack2(siluf_(g[2]) * u[2], siluf_(g[3]) * u[3]);
;             *(uint2*)(e.b0 + (row * (unsigned)DFF + hc)) = o;
;           }
.Lsw_last:
	v_mfma_f32_16x16x32_bf16 v[134:137], v[194:197], v[156:159], v[134:137]
	v_mfma_f32_16x16x32_bf16 v[130:133], v[198:201], v[156:159], v[130:133]
	v_mfma_f32_16x16x32_bf16 v[126:129], v[202:205], v[156:159], v[126:129]
	v_mfma_f32_16x16x32_bf16 v[122:125], v[226:229], v[156:159], v[122:125]
	v_mfma_f32_16x16x32_bf16 v[118:121], v[194:197], v[166:169], v[118:121]
	v_mfma_f32_16x16x32_bf16 v[114:117], v[198:201], v[166:169], v[114:117]
	v_mfma_f32_16x16x32_bf16 v[110:113], v[202:205], v[166:169], v[110:113]
	v_mfma_f32_16x16x32_bf16 v[106:109], v[226:229], v[166:169], v[106:109]
	v_mfma_f32_16x16x32_bf16 v[102:105], v[194:197], v[170:173], v[102:105]
	v_mfma_f32_16x16x32_bf16 v[98:101], v[198:201], v[170:173], v[98:101]
	v_mfma_f32_16x16x32_bf16 v[94:97], v[202:205], v[170:173], v[94:97]
	v_mfma_f32_16x16x32_bf16 v[90:93], v[226:229], v[170:173], v[90:93]
	v_mfma_f32_16x16x32_bf16 v[86:89], v[194:197], v[174:177], v[86:89]
	v_mfma_f32_16x16x32_bf16 v[82:85], v[198:201], v[174:177], v[82:85]
	v_mfma_f32_16x16x32_bf16 v[78:81], v[202:205], v[174:177], v[78:81]
	v_mfma_f32_16x16x32_bf16 v[74:77], v[226:229], v[174:177], v[74:77]
	v_mfma_f32_16x16x32_bf16 v[70:73], v[194:197], v[178:181], v[70:73]
	v_mfma_f32_16x16x32_bf16 v[66:69], v[198:201], v[178:181], v[66:69]
	v_mfma_f32_16x16x32_bf16 v[62:65], v[202:205], v[178:181], v[62:65]
	v_mfma_f32_16x16x32_bf16 v[58:61], v[226:229], v[178:181], v[58:61]
	v_mfma_f32_16x16x32_bf16 v[54:57], v[194:197], v[182:185], v[54:57]
	v_mfma_f32_16x16x32_bf16 v[50:53], v[198:201], v[182:185], v[50:53]
	v_mfma_f32_16x16x32_bf16 v[46:49], v[202:205], v[182:185], v[46:49]
	v_mfma_f32_16x16x32_bf16 v[42:45], v[226:229], v[182:185], v[42:45]
	v_mfma_f32_16x16x32_bf16 v[38:41], v[194:197], v[186:189], v[38:41]
	v_mfma_f32_16x16x32_bf16 v[34:37], v[198:201], v[186:189], v[34:37]
	v_mfma_f32_16x16x32_bf16 v[30:33], v[202:205], v[186:189], v[30:33]
	v_mfma_f32_16x16x32_bf16 v[26:29], v[226:229], v[186:189], v[26:29]
	v_mfma_f32_16x16x32_bf16 v[22:25], v[194:197], v[190:193], v[22:25]
	v_mfma_f32_16x16x32_bf16 v[18:21], v[198:201], v[190:193], v[18:21]
	v_mfma_f32_16x16x32_bf16 v[14:17], v[202:205], v[190:193], v[14:17]
	v_mfma_f32_16x16x32_bf16 v[10:13], v[226:229], v[190:193], v[10:13]
	v_or_b32_e32 v8, s8, v148
	v_lshrrev_b32_e32 v8, 1, v8
	v_add_u32_e32 v142, s7, v150
	v_or_b32_e32 v8, v8, v149
	s_movk_i32 s4, 0xb00
	v_mad_u64_u32 v[142:143], s[4:5], v142, s4, v[8:9]
	v_mul_f32_e32 v8, 0xbfb8aa3b, v134
	v_exp_f32_e32 v8, v8
	v_mov_b32_e32 v143, v9
	v_add_f32_e32 v8, 1.0, v8
	v_rcp_f32_e32 v144, v8
	v_mul_f32_e32 v8, 0xbfb8aa3b, v135
	v_exp_f32_e32 v8, v8
	s_nop 0
	v_add_f32_e32 v8, 1.0, v8
	v_rcp_f32_e32 v145, v8
	v_mul_f32_e32 v8, 0xbfb8aa3b, v136
	v_exp_f32_e32 v8, v8
	v_pk_mul_f32 v[134:135], v[134:135], v[144:145]
	s_nop 0
	v_pk_mul_f32 v[130:131], v[130:131], v[134:135]
	v_add_f32_e32 v8, 1.0, v8
	v_rcp_f32_e32 v134, v8
	v_mul_f32_e32 v8, 0xbfb8aa3b, v137
	v_exp_f32_e32 v8, v8
	v_cvt_pk_bf16_f32 v130, v130, v131
	v_add_f32_e32 v8, 1.0, v8
	v_rcp_f32_e32 v135, v8
	v_mul_f32_e32 v8, 0xbfb8aa3b, v126
	v_exp_f32_e32 v8, v8
	v_pk_mul_f32 v[134:135], v[136:137], v[134:135]
	s_nop 0
	v_pk_mul_f32 v[132:133], v[132:133], v[134:135]
	v_add_f32_e32 v8, 1.0, v8
	v_cvt_pk_bf16_f32 v131, v132, v133
	v_lshl_add_u64 v[132:133], v[142:143], 1, s[52:53]
	global_store_dwordx2 v[132:133], v[130:131], off
	v_rcp_f32_e32 v130, v8
	v_mul_f32_e32 v8, 0xbfb8aa3b, v127
	v_exp_f32_e32 v8, v8
	s_nop 0
	v_add_f32_e32 v8, 1.0, v8
	v_rcp_f32_e32 v131, v8
	v_mul_f32_e32 v8, 0xbfb8aa3b, v128
	v_exp_f32_e32 v8, v8
	v_pk_mul_f32 v[126:127], v[126:127], v[130:131]
	s_nop 0
	v_pk_mul_f32 v[122:123], v[122:123], v[126:127]
	v_add_f32_e32 v8, 1.0, v8
	v_rcp_f32_e32 v126, v8
	v_mul_f32_e32 v8, 0xbfb8aa3b, v129
	v_exp_f32_e32 v8, v8
	v_cvt_pk_bf16_f32 v122, v122, v123
	v_add_f32_e32 v8, 1.0, v8
	v_rcp_f32_e32 v127, v8
	v_or_b32_e32 v8, 16, v142
	v_pk_mul_f32 v[126:127], v[128:129], v[126:127]
	s_nop 0
	v_pk_mul_f32 v[124:125], v[124:125], v[126:127]
	s_nop 0
	v_cvt_pk_bf16_f32 v123, v124, v125
	v_lshl_add_u64 v[124:125], v[8:9], 1, s[52:53]
	global_store_dwordx2 v[124:125], v[122:123], off
	v_mul_f32_e32 v122, 0xbfb8aa3b, v118
	v_mul_f32_e32 v123, 0xbfb8aa3b, v119
	v_exp_f32_e32 v122, v122
	v_exp_f32_e32 v123, v123
	v_add_u32_e32 v8, 0xb000, v142
	v_add_f32_e32 v122, 1.0, v122
	v_add_f32_e32 v123, 1.0, v123
	v_rcp_f32_e32 v122, v122
	v_rcp_f32_e32 v123, v123
	s_nop 0
	v_pk_mul_f32 v[118:119], v[118:119], v[122:123]
	s_nop 0
	v_pk_mul_f32 v[114:115], v[114:115], v[118:119]
	s_nop 0
	v_cvt_pk_bf16_f32 v114, v114, v115
	v_mul_f32_e32 v115, 0xbfb8aa3b, v120
	v_exp_f32_e32 v115, v115
	s_nop 0
	v_add_f32_e32 v115, 1.0, v115
	v_rcp_f32_e32 v118, v115
	v_mul_f32_e32 v115, 0xbfb8aa3b, v121
	v_exp_f32_e32 v115, v115
	s_nop 0
	v_add_f32_e32 v115, 1.0, v115
	v_rcp_f32_e32 v119, v115
	s_nop 0
	v_pk_mul_f32 v[118:119], v[120:121], v[118:119]
	s_nop 0
	v_pk_mul_f32 v[116:117], v[116:117], v[118:119]
	s_nop 0
	v_cvt_pk_bf16_f32 v115, v116, v117
	v_lshl_add_u64 v[116:117], v[8:9], 1, s[52:53]
	v_mul_f32_e32 v8, 0xbfb8aa3b, v110
	v_exp_f32_e32 v8, v8
	global_store_dwordx2 v[116:117], v[114:115], off
	v_add_f32_e32 v8, 1.0, v8
	v_rcp_f32_e32 v114, v8
	v_mul_f32_e32 v8, 0xbfb8aa3b, v111
	v_exp_f32_e32 v8, v8
	s_nop 0
	v_add_f32_e32 v8, 1.0, v8
	v_rcp_f32_e32 v115, v8
	v_mul_f32_e32 v8, 0xbfb8aa3b, v112
	v_exp_f32_e32 v8, v8
	v_pk_mul_f32 v[110:111], v[110:111], v[114:115]
	s_nop 0
	v_pk_mul_f32 v[106:107], v[106:107], v[110:111]
	v_add_f32_e32 v8, 1.0, v8
	v_rcp_f32_e32 v110, v8
	v_mul_f32_e32 v8, 0xbfb8aa3b, v113
	v_exp_f32_e32 v8, v8
	v_cvt_pk_bf16_f32 v106, v106, v107
; __device__ __forceinline__ float siluf_(float x) { return x * __builtin_amdgcn_rcpf(1.f + __expf(-x)); }
;     ...
;         } else if constexpr (EPI == EPI_SWIGLU) {
; #pragma unroll
;           for (int np = 0; np < 2; np++) {
;             const unsigned hc = ((unsigned)(n0 + wn * 64) >> 1) + np * 16 + fq * 4;
;             const f32x4 g = acc[mi][2 * np], u = acc[mi][2 * np + 1];
;             uint2 o;
;             o.x = pack2(siluf_(g[0]) * u[0], siluf_(g[1]) * u[1]);
;             o.y = pack2(siluf_(g[2]) * u[2], siluf_(g[3]) * u[3]);
;             *(uint2*)(e.b0 + (row * (unsigned)DFF + hc)) = o;
;           }
	v_add_f32_e32 v8, 1.0, v8
	v_rcp_f32_e32 v111, v8
	v_add_u32_e32 v8, 0xb010, v142
	v_pk_mul_f32 v[110:111], v[112:113], v[110:111]
	s_nop 0
	v_pk_mul_f32 v[108:109], v[108:109], v[110:111]
	s_nop 0
	v_cvt_pk_bf16_f32 v107, v108, v109
	v_lshl_add_u64 v[108:109], v[8:9], 1, s[52:53]
	global_store_dwordx2 v[108:109], v[106:107], off
	v_mul_f32_e32 v106, 0xbfb8aa3b, v102
	v_mul_f32_e32 v107, 0xbfb8aa3b, v103
	v_exp_f32_e32 v106, v106
	v_exp_f32_e32 v107, v107
	v_add_u32_e32 v8, 0x16000, v142
	v_add_f32_e32 v106, 1.0, v106
	v_add_f32_e32 v107, 1.0, v107
	v_rcp_f32_e32 v106, v106
	v_rcp_f32_e32 v107, v107
	s_nop 0
	v_pk_mul_f32 v[102:103], v[102:103], v[106:107]
	s_nop 0
	v_pk_mul_f32 v[98:99], v[98:99], v[102:103]
	s_nop 0
	v_cvt_pk_bf16_f32 v98, v98, v99
	v_mul_f32_e32 v99, 0xbfb8aa3b, v104
	v_exp_f32_e32 v99, v99
	s_nop 0
	v_add_f32_e32 v99, 1.0, v99
	v_rcp_f32_e32 v102, v99
	v_mul_f32_e32 v99, 0xbfb8aa3b, v105
	v_exp_f32_e32 v99, v99
	s_nop 0
	v_add_f32_e32 v99, 1.0, v99
	v_rcp_f32_e32 v103, v99
	s_nop 0
	v_pk_mul_f32 v[102:103], v[104:105], v[102:103]
	s_nop 0
	v_pk_mul_f32 v[100:101], v[100:101], v[102:103]
	s_nop 0
	v_cvt_pk_bf16_f32 v99, v100, v101
	v_lshl_add_u64 v[100:101], v[8:9], 1, s[52:53]
	v_mul_f32_e32 v8, 0xbfb8aa3b, v94
	v_exp_f32_e32 v8, v8
	global_store_dwordx2 v[100:101], v[98:99], off
	v_add_f32_e32 v8, 1.0, v8
	v_rcp_f32_e32 v98, v8
	v_mul_f32_e32 v8, 0xbfb8aa3b, v95
	v_exp_f32_e32 v8, v8
	s_nop 0
	v_add_f32_e32 v8, 1.0, v8
	v_rcp_f32_e32 v99, v8
	v_mul_f32_e32 v8, 0xbfb8aa3b, v96
	v_exp_f32_e32 v8, v8
	v_pk_mul_f32 v[94:95], v[94:95], v[98:99]
	s_nop 0
	v_pk_mul_f32 v[90:91], v[90:91], v[94:95]
	v_add_f32_e32 v8, 1.0, v8
	v_rcp_f32_e32 v94, v8
	v_mul_f32_e32 v8, 0xbfb8aa3b, v97
	v_exp_f32_e32 v8, v8
	v_cvt_pk_bf16_f32 v90, v90, v91
	v_add_f32_e32 v8, 1.0, v8
	v_rcp_f32_e32 v95, v8
	v_add_u32_e32 v8, 0x16010, v142
	v_pk_mul_f32 v[94:95], v[96:97], v[94:95]
	s_nop 0
	v_pk_mul_f32 v[92:93], v[92:93], v[94:95]
	s_nop 0
	v_cvt_pk_bf16_f32 v91, v92, v93
	v_lshl_add_u64 v[92:93], v[8:9], 1, s[52:53]
	global_store_dwordx2 v[92:93], v[90:91], off
	v_mul_f32_e32 v90, 0xbfb8aa3b, v86
	v_mul_f32_e32 v91, 0xbfb8aa3b, v87
	v_exp_f32_e32 v90, v90
	v_exp_f32_e32 v91, v91
	v_add_u32_e32 v8, 0x21000, v142
	v_add_f32_e32 v90, 1.0, v90
	v_add_f32_e32 v91, 1.0, v91
	v_rcp_f32_e32 v90, v90
	v_rcp_f32_e32 v91, v91
	s_nop 0
	v_pk_mul_f32 v[86:87], v[86:87], v[90:91]
	s_nop 0
	v_pk_mul_f32 v[82:83], v[82:83], v[86:87]
	s_nop 0
	v_cvt_pk_bf16_f32 v82, v82, v83
	v_mul_f32_e32 v83, 0xbfb8aa3b, v88
	v_exp_f32_e32 v83, v83
	s_nop 0
	v_add_f32_e32 v83, 1.0, v83
	v_rcp_f32_e32 v86, v83
	v_mul_f32_e32 v83, 0xbfb8aa3b, v89
	v_exp_f32_e32 v83, v83
	s_nop 0
	v_add_f32_e32 v83, 1.0, v83
	v_rcp_f32_e32 v87, v83
	s_nop 0
	v_pk_mul_f32 v[86:87], v[88:89], v[86:87]
	s_nop 0
	v_pk_mul_f32 v[84:85], v[84:85], v[86:87]
	s_nop 0
	v_cvt_pk_bf16_f32 v83, v84, v85
	v_lshl_add_u64 v[84:85], v[8:9], 1, s[52:53]
	v_mul_f32_e32 v8, 0xbfb8aa3b, v78
	v_exp_f32_e32 v8, v8
	global_store_dwordx2 v[84:85], v[82:83], off
	v_add_f32_e32 v8, 1.0, v8
	v_rcp_f32_e32 v82, v8
	v_mul_f32_e32 v8, 0xbfb8aa3b, v79
	v_exp_f32_e32 v8, v8
	s_nop 0
	v_add_f32_e32 v8, 1.0, v8
	v_rcp_f32_e32 v83, v8
	v_mul_f32_e32 v8, 0xbfb8aa3b, v80
	v_exp_f32_e32 v8, v8
	v_pk_mul_f32 v[78:79], v[78:79], v[82:83]
	s_nop 0
	v_pk_mul_f32 v[74:75], v[74:75], v[78:79]
	v_add_f32_e32 v8, 1.0, v8
	v_rcp_f32_e32 v78, v8
	v_mul_f32_e32 v8, 0xbfb8aa3b, v81
	v_exp_f32_e32 v8, v8
	v_cvt_pk_bf16_f32 v74, v74, v75
	v_add_f32_e32 v8, 1.0, v8
	v_rcp_f32_e32 v79, v8
	v_add_u32_e32 v8, 0x21010, v142
	v_pk_mul_f32 v[78:79], v[80:81], v[78:79]
	s_nop 0
	v_pk_mul_f32 v[76:77], v[76:77], v[78:79]
	s_nop 0
	v_cvt_pk_bf16_f32 v75, v76, v77
	v_lshl_add_u64 v[76:77], v[8:9], 1, s[52:53]
	global_store_dwordx2 v[76:77], v[74:75], off
	v_mul_f32_e32 v74, 0xbfb8aa3b, v70
	v_mul_f32_e32 v75, 0xbfb8aa3b, v71
	v_exp_f32_e32 v74, v74
	v_exp_f32_e32 v75, v75
	v_add_u32_e32 v8, 0x2c000, v142
	v_add_f32_e32 v74, 1.0, v74
	v_add_f32_e32 v75, 1.0, v75
	v_rcp_f32_e32 v74, v74
	v_rcp_f32_e32 v75, v75
	s_nop 0
	v_pk_mul_f32 v[70:71], v[70:71], v[74:75]
	s_nop 0
	v_pk_mul_f32 v[66:67], v[66:67], v[70:71]
	s_nop 0
	v_cvt_pk_bf16_f32 v66, v66, v67
	v_mul_f32_e32 v67, 0xbfb8aa3b, v72
	v_exp_f32_e32 v67, v67
	s_nop 0
	v_add_f32_e32 v67, 1.0, v67
	v_rcp_f32_e32 v70, v67
	v_mul_f32_e32 v67, 0xbfb8aa3b, v73
	v_exp_f32_e32 v67, v67
	s_nop 0
	v_add_f32_e32 v67, 1.0, v67
	v_rcp_f32_e32 v71, v67
	s_nop 0
	v_pk_mul_f32 v[70:71], v[72:73], v[70:71]
	s_nop 0
	v_pk_mul_f32 v[68:69], v[68:69], v[70:71]
	s_nop 0
	v_cvt_pk_bf16_f32 v67, v68, v69
	v_lshl_add_u64 v[68:69], v[8:9], 1, s[52:53]
	v_mul_f32_e32 v8, 0xbfb8aa3b, v62
	v_exp_f32_e32 v8, v8
	global_store_dwordx2 v[68:69], v[66:67], off
	v_add_f32_e32 v8, 1.0, v8
	v_rcp_f32_e32 v66, v8
	v_mul_f32_e32 v8, 0xbfb8aa3b, v63
	v_exp_f32_e32 v8, v8
	s_nop 0
	v_add_f32_e32 v8, 1.0, v8
	v_rcp_f32_e32 v67, v8
	v_mul_f32_e32 v8, 0xbfb8aa3b, v64
	v_exp_f32_e32 v8, v8
	v_pk_mul_f32 v[62:63], v[62:63], v[66:67]
	s_nop 0
	v_pk_mul_f32 v[58:59], v[58:59], v[62:63]
	v_add_f32_e32 v8, 1.0, v8
	v_rcp_f32_e32 v62, v8
	v_mul_f32_e32 v8, 0xbfb8aa3b, v65
	v_exp_f32_e32 v8, v8
	v_cvt_pk_bf16_f32 v58, v58, v59
	v_add_f32_e32 v8, 1.0, v8
	v_rcp_f32_e32 v63, v8
	v_add_u32_e32 v8, 0x2c010, v142
	v_pk_mul_f32 v[62:63], v[64:65], v[62:63]
	s_nop 0
; __device__ __forceinline__ float siluf_(float x) { return x * __builtin_amdgcn_rcpf(1.f + __expf(-x)); }
;     ...
;   for (int it = 0;; it++) {
;     int tile;
;     if (nb == 512) tile = ((it * 8 + (bid & 7)) << 6) + (bid >> 3); else tile = it * nb + bid;
;     tile += tbeg;
;     if (tile >= MTX * ntn || tile >= tend) break;
;     ...
;         } else if constexpr (EPI == EPI_SWIGLU) {
; #pragma unroll
;           for (int np = 0; np < 2; np++) {
;             const unsigned hc = ((unsigned)(n0 + wn * 64) >> 1) + np * 16 + fq * 4;
;             const f32x4 g = acc[mi][2 * np], u = acc[mi][2 * np + 1];
;             uint2 o;
;             o.x = pack2(siluf_(g[0]) * u[0], siluf_(g[1]) * u[1]);
;             o.y = pack2(siluf_(g[2]) * u[2], siluf_(g[3]) * u[3]);
;             *(uint2*)(e.b0 + (row * (unsigned)DFF + hc)) = o;
;           }
	v_pk_mul_f32 v[60:61], v[60:61], v[62:63]
	s_nop 0
	v_cvt_pk_bf16_f32 v59, v60, v61
	v_lshl_add_u64 v[60:61], v[8:9], 1, s[52:53]
	global_store_dwordx2 v[60:61], v[58:59], off
	v_mul_f32_e32 v58, 0xbfb8aa3b, v54
	v_mul_f32_e32 v59, 0xbfb8aa3b, v55
	v_exp_f32_e32 v58, v58
	v_exp_f32_e32 v59, v59
	v_add_u32_e32 v8, 0x37000, v142
	v_add_f32_e32 v58, 1.0, v58
	v_add_f32_e32 v59, 1.0, v59
	v_rcp_f32_e32 v58, v58
	v_rcp_f32_e32 v59, v59
	s_nop 0
	v_pk_mul_f32 v[54:55], v[54:55], v[58:59]
	s_nop 0
	v_pk_mul_f32 v[50:51], v[50:51], v[54:55]
	s_nop 0
	v_cvt_pk_bf16_f32 v50, v50, v51
	v_mul_f32_e32 v51, 0xbfb8aa3b, v56
	v_exp_f32_e32 v51, v51
	s_nop 0
	v_add_f32_e32 v51, 1.0, v51
	v_rcp_f32_e32 v54, v51
	v_mul_f32_e32 v51, 0xbfb8aa3b, v57
	v_exp_f32_e32 v51, v51
	s_nop 0
	v_add_f32_e32 v51, 1.0, v51
	v_rcp_f32_e32 v55, v51
	s_nop 0
	v_pk_mul_f32 v[54:55], v[56:57], v[54:55]
	s_nop 0
	v_pk_mul_f32 v[52:53], v[52:53], v[54:55]
	s_nop 0
	v_cvt_pk_bf16_f32 v51, v52, v53
	v_lshl_add_u64 v[52:53], v[8:9], 1, s[52:53]
	v_mul_f32_e32 v8, 0xbfb8aa3b, v46
	v_exp_f32_e32 v8, v8
	global_store_dwordx2 v[52:53], v[50:51], off
	v_add_f32_e32 v8, 1.0, v8
	v_rcp_f32_e32 v50, v8
	v_mul_f32_e32 v8, 0xbfb8aa3b, v47
	v_exp_f32_e32 v8, v8
	s_nop 0
	v_add_f32_e32 v8, 1.0, v8
	v_rcp_f32_e32 v51, v8
	v_mul_f32_e32 v8, 0xbfb8aa3b, v48
	v_exp_f32_e32 v8, v8
	v_pk_mul_f32 v[46:47], v[46:47], v[50:51]
	s_nop 0
	v_pk_mul_f32 v[42:43], v[42:43], v[46:47]
	v_add_f32_e32 v8, 1.0, v8
	v_rcp_f32_e32 v46, v8
	v_mul_f32_e32 v8, 0xbfb8aa3b, v49
	v_exp_f32_e32 v8, v8
	v_cvt_pk_bf16_f32 v42, v42, v43
	v_add_f32_e32 v8, 1.0, v8
	v_rcp_f32_e32 v47, v8
	v_add_u32_e32 v8, 0x37010, v142
	v_pk_mul_f32 v[46:47], v[48:49], v[46:47]
	s_nop 0
	v_pk_mul_f32 v[44:45], v[44:45], v[46:47]
	s_nop 0
	v_cvt_pk_bf16_f32 v43, v44, v45
	v_lshl_add_u64 v[44:45], v[8:9], 1, s[52:53]
	global_store_dwordx2 v[44:45], v[42:43], off
	v_mul_f32_e32 v42, 0xbfb8aa3b, v38
	v_mul_f32_e32 v43, 0xbfb8aa3b, v39
	v_exp_f32_e32 v42, v42
	v_exp_f32_e32 v43, v43
	v_add_u32_e32 v8, 0x42000, v142
	v_add_f32_e32 v42, 1.0, v42
	v_add_f32_e32 v43, 1.0, v43
	v_rcp_f32_e32 v42, v42
	v_rcp_f32_e32 v43, v43
	s_nop 0
	v_pk_mul_f32 v[38:39], v[38:39], v[42:43]
	s_nop 0
	v_pk_mul_f32 v[34:35], v[34:35], v[38:39]
	s_nop 0
	v_cvt_pk_bf16_f32 v34, v34, v35
	v_mul_f32_e32 v35, 0xbfb8aa3b, v40
	v_exp_f32_e32 v35, v35
	s_nop 0
	v_add_f32_e32 v35, 1.0, v35
	v_rcp_f32_e32 v38, v35
	v_mul_f32_e32 v35, 0xbfb8aa3b, v41
	v_exp_f32_e32 v35, v35
	s_nop 0
	v_add_f32_e32 v35, 1.0, v35
	v_rcp_f32_e32 v39, v35
	s_nop 0
	v_pk_mul_f32 v[38:39], v[40:41], v[38:39]
	s_nop 0
	v_pk_mul_f32 v[36:37], v[36:37], v[38:39]
	s_nop 0
	v_cvt_pk_bf16_f32 v35, v36, v37
	v_lshl_add_u64 v[36:37], v[8:9], 1, s[52:53]
	v_mul_f32_e32 v8, 0xbfb8aa3b, v30
	v_exp_f32_e32 v8, v8
	global_store_dwordx2 v[36:37], v[34:35], off
	v_add_f32_e32 v8, 1.0, v8
	v_rcp_f32_e32 v34, v8
	v_mul_f32_e32 v8, 0xbfb8aa3b, v31
	v_exp_f32_e32 v8, v8
	s_nop 0
	v_add_f32_e32 v8, 1.0, v8
	v_rcp_f32_e32 v35, v8
	v_mul_f32_e32 v8, 0xbfb8aa3b, v32
	v_exp_f32_e32 v8, v8
	v_pk_mul_f32 v[30:31], v[30:31], v[34:35]
	s_nop 0
	v_pk_mul_f32 v[26:27], v[26:27], v[30:31]
	v_add_f32_e32 v8, 1.0, v8
	v_rcp_f32_e32 v30, v8
	v_mul_f32_e32 v8, 0xbfb8aa3b, v33
	v_exp_f32_e32 v8, v8
	v_cvt_pk_bf16_f32 v26, v26, v27
	v_add_f32_e32 v8, 1.0, v8
	v_rcp_f32_e32 v31, v8
	v_add_u32_e32 v8, 0x42010, v142
	v_pk_mul_f32 v[30:31], v[32:33], v[30:31]
	s_nop 0
	v_pk_mul_f32 v[28:29], v[28:29], v[30:31]
	s_nop 0
	v_cvt_pk_bf16_f32 v27, v28, v29
	v_lshl_add_u64 v[28:29], v[8:9], 1, s[52:53]
	global_store_dwordx2 v[28:29], v[26:27], off
	v_mul_f32_e32 v26, 0xbfb8aa3b, v22
	v_mul_f32_e32 v27, 0xbfb8aa3b, v23
	v_exp_f32_e32 v26, v26
	v_exp_f32_e32 v27, v27
	v_add_u32_e32 v8, 0x4d000, v142
	v_add_f32_e32 v26, 1.0, v26
	v_add_f32_e32 v27, 1.0, v27
	v_rcp_f32_e32 v26, v26
	v_rcp_f32_e32 v27, v27
	s_nop 0
	v_pk_mul_f32 v[22:23], v[22:23], v[26:27]
	s_nop 0
	v_pk_mul_f32 v[18:19], v[18:19], v[22:23]
	s_nop 0
	v_cvt_pk_bf16_f32 v18, v18, v19
	v_mul_f32_e32 v19, 0xbfb8aa3b, v24
	v_exp_f32_e32 v19, v19
	s_nop 0
	v_add_f32_e32 v19, 1.0, v19
	v_rcp_f32_e32 v22, v19
	v_mul_f32_e32 v19, 0xbfb8aa3b, v25
	v_exp_f32_e32 v19, v19
	s_nop 0
	v_add_f32_e32 v19, 1.0, v19
	v_rcp_f32_e32 v23, v19
	s_nop 0
	v_pk_mul_f32 v[22:23], v[24:25], v[22:23]
	s_nop 0
	v_pk_mul_f32 v[20:21], v[20:21], v[22:23]
	s_nop 0
	v_cvt_pk_bf16_f32 v19, v20, v21
	v_lshl_add_u64 v[20:21], v[8:9], 1, s[52:53]
	v_mul_f32_e32 v8, 0xbfb8aa3b, v14
	v_exp_f32_e32 v8, v8
	global_store_dwordx2 v[20:21], v[18:19], off
	v_add_f32_e32 v8, 1.0, v8
	v_rcp_f32_e32 v18, v8
	v_mul_f32_e32 v8, 0xbfb8aa3b, v15
	v_exp_f32_e32 v8, v8
	s_nop 0
	v_add_f32_e32 v8, 1.0, v8
	v_rcp_f32_e32 v19, v8
	v_mul_f32_e32 v8, 0xbfb8aa3b, v16
	v_exp_f32_e32 v8, v8
	v_pk_mul_f32 v[14:15], v[14:15], v[18:19]
	s_nop 0
	v_pk_mul_f32 v[10:11], v[10:11], v[14:15]
	v_add_f32_e32 v8, 1.0, v8
	v_rcp_f32_e32 v14, v8
	v_mul_f32_e32 v8, 0xbfb8aa3b, v17
	v_exp_f32_e32 v8, v8
	v_cvt_pk_bf16_f32 v10, v10, v11
	v_add_f32_e32 v8, 1.0, v8
	v_rcp_f32_e32 v15, v8
	v_add_u32_e32 v8, 0x4d010, v142
	v_pk_mul_f32 v[14:15], v[16:17], v[14:15]
	s_nop 0
	v_pk_mul_f32 v[12:13], v[12:13], v[14:15]
	s_nop 0
	v_cvt_pk_bf16_f32 v11, v12, v13
	v_lshl_add_u64 v[12:13], v[8:9], 1, s[52:53]
	global_store_dwordx2 v[12:13], v[10:11], off
	s_add_i32 s6, s6, 1
	s_mov_b64 s[4:5], 0
	s_branch .LBB0_2615
